# baseline (speedup 1.0000x reference)
.LBB0_252:
	s_or_b64 exec, exec, s[46:47]
	v_and_b32_e32 v131, 15, v204
	v_lshlrev_b32_e32 v4, 2, v204
	v_and_b32_e32 v2, 48, v204
	v_lshlrev_b32_e32 v3, 6, v131
	v_and_b32_e32 v4, 32, v4
	v_bitop3_b32 v238, v2, v4, v3 bitop3:0x36
	v_lshlrev_b32_e32 v2, 13, v130
	v_add3_u32 v237, 0, v2, v238
	v_lshlrev_b32_e32 v2, 6, v204
	v_and_b32_e32 v2, 0x3000, v2
	s_add_i32 s2, 0, 0x10000
	v_add_u32_e32 v239, s2, v2
	s_lshr_b32 s2, s31, 26
	s_add_i32 s2, s30, s2
	v_add_u32_e32 v242, 0x18000, v232
	s_ashr_i32 s33, s2, 6
	v_readfirstlane_b32 s2, v242
	v_add_u32_e32 v243, 0x1a000, v232
	s_mov_b32 s46, s26
	s_mov_b32 s47, s27
	s_mov_b32 m0, s2
	v_readfirstlane_b32 s31, v243
	v_add_u32_e32 v244, 0x8000, v232
	s_waitcnt vmcnt(0)
	s_barrier
	buffer_load_dwordx4 v0, s[44:47], s17 offen lds
	s_add_i32 s2, s8, 0x80
	s_mov_b32 m0, s31
	v_readfirstlane_b32 s31, v244
	v_add_u32_e32 v245, 0xa000, v232
	buffer_load_dwordx4 v0, s[44:47], s2 offen lds
	s_mov_b32 m0, s31
	v_readfirstlane_b32 s31, v245
	v_add_u32_e32 v246, 0x1c000, v232
	buffer_load_dwordx4 v0, s[24:27], s17 offen lds
	s_mov_b32 m0, s31
	s_lshl_b32 s58, s30, 8
	v_readfirstlane_b32 s31, v246
	v_add_u32_e32 v247, 0x1e000, v232
	buffer_load_dwordx4 v0, s[24:27], s2 offen lds
	s_or_b32 s2, s58, 0x80
	s_mov_b32 m0, s31
	v_readfirstlane_b32 s31, v247
	buffer_load_dwordx4 v0, s[44:47], s2 offen lds
	s_add_i32 s2, s2, s8
	s_mov_b32 m0, s31
	v_mov_b32_e32 v5, 0
	buffer_load_dwordx4 v0, s[44:47], s2 offen lds
	s_waitcnt vmcnt(6)
	s_cmpk_lt_i32 s30, 0xc0
	v_add_u32_e32 v241, 0xc000, v232
	v_add_u32_e32 v240, 0xe000, v232
	v_mov_b32_e32 v4, v5
	v_mov_b32_e32 v3, v5
	v_mov_b32_e32 v2, v5
	v_mov_b32_e32 v9, v5
	v_mov_b32_e32 v8, v5
	v_mov_b32_e32 v7, v5
	v_mov_b32_e32 v6, v5
	v_mov_b32_e32 v13, v5
	v_mov_b32_e32 v12, v5
	v_mov_b32_e32 v11, v5
	v_mov_b32_e32 v10, v5
	v_mov_b32_e32 v17, v5
	v_mov_b32_e32 v16, v5
	v_mov_b32_e32 v15, v5
	v_mov_b32_e32 v14, v5
	s_waitcnt vmcnt(13)
	v_mov_b32_e32 v21, v5
	v_mov_b32_e32 v20, v5
	v_mov_b32_e32 v19, v5
	v_mov_b32_e32 v18, v5
	s_waitcnt vmcnt(12)
	v_mov_b32_e32 v25, v5
	v_mov_b32_e32 v24, v5
	v_mov_b32_e32 v23, v5
	v_mov_b32_e32 v22, v5
	s_waitcnt vmcnt(11)
	v_mov_b32_e32 v29, v5
	v_mov_b32_e32 v28, v5
	v_mov_b32_e32 v27, v5
	v_mov_b32_e32 v26, v5
	s_waitcnt vmcnt(10)
	v_mov_b32_e32 v33, v5
	v_mov_b32_e32 v32, v5
	v_mov_b32_e32 v31, v5
	v_mov_b32_e32 v30, v5
	v_mov_b32_e32 v37, v5
	v_mov_b32_e32 v36, v5
	v_mov_b32_e32 v35, v5
	v_mov_b32_e32 v34, v5
	v_mov_b32_e32 v41, v5
	v_mov_b32_e32 v40, v5
	v_mov_b32_e32 v39, v5
	v_mov_b32_e32 v38, v5
	v_mov_b32_e32 v45, v5
	v_mov_b32_e32 v44, v5
	v_mov_b32_e32 v43, v5
	v_mov_b32_e32 v42, v5
	v_mov_b32_e32 v49, v5
	v_mov_b32_e32 v48, v5
	v_mov_b32_e32 v47, v5
	v_mov_b32_e32 v46, v5
	v_mov_b32_e32 v53, v5
	v_mov_b32_e32 v52, v5
	v_mov_b32_e32 v51, v5
	v_mov_b32_e32 v50, v5
	v_mov_b32_e32 v57, v5
	v_mov_b32_e32 v56, v5
	v_mov_b32_e32 v55, v5
	v_mov_b32_e32 v54, v5
	v_mov_b32_e32 v61, v5
	v_mov_b32_e32 v60, v5
	v_mov_b32_e32 v59, v5
	v_mov_b32_e32 v58, v5
	v_mov_b32_e32 v65, v5
	v_mov_b32_e32 v64, v5
	v_mov_b32_e32 v63, v5
	v_mov_b32_e32 v62, v5
	v_mov_b32_e32 v129, v5
	v_mov_b32_e32 v128, v5
	v_mov_b32_e32 v127, v5
	v_mov_b32_e32 v126, v5
	v_mov_b32_e32 v125, v5
	v_mov_b32_e32 v124, v5
	v_mov_b32_e32 v123, v5
	v_mov_b32_e32 v122, v5
	v_mov_b32_e32 v121, v5
	v_mov_b32_e32 v120, v5
	v_mov_b32_e32 v119, v5
	v_mov_b32_e32 v118, v5
	v_mov_b32_e32 v117, v5
	v_mov_b32_e32 v116, v5
	v_mov_b32_e32 v115, v5
	v_mov_b32_e32 v114, v5
	v_mov_b32_e32 v113, v5
	v_mov_b32_e32 v112, v5
	v_mov_b32_e32 v111, v5
	v_mov_b32_e32 v110, v5
	v_mov_b32_e32 v109, v5
	v_mov_b32_e32 v108, v5
	v_mov_b32_e32 v107, v5
	v_mov_b32_e32 v106, v5
	v_mov_b32_e32 v105, v5
	v_mov_b32_e32 v104, v5
	v_mov_b32_e32 v103, v5
	v_mov_b32_e32 v102, v5
	v_mov_b32_e32 v101, v5
	v_mov_b32_e32 v100, v5
	v_mov_b32_e32 v99, v5
	v_mov_b32_e32 v98, v5
	v_mov_b32_e32 v97, v5
	v_mov_b32_e32 v96, v5
	v_mov_b32_e32 v95, v5
	v_mov_b32_e32 v94, v5
	v_mov_b32_e32 v93, v5
	v_mov_b32_e32 v92, v5
	v_mov_b32_e32 v91, v5
	v_mov_b32_e32 v90, v5
	v_mov_b32_e32 v89, v5
	v_mov_b32_e32 v88, v5
	v_mov_b32_e32 v87, v5
	v_mov_b32_e32 v86, v5
	v_mov_b32_e32 v85, v5
	v_mov_b32_e32 v84, v5
	v_mov_b32_e32 v83, v5
	v_mov_b32_e32 v82, v5
	v_mov_b32_e32 v81, v5
	v_mov_b32_e32 v80, v5
	v_mov_b32_e32 v79, v5
	v_mov_b32_e32 v78, v5
	v_mov_b32_e32 v77, v5
	v_mov_b32_e32 v76, v5
	v_mov_b32_e32 v75, v5
	v_mov_b32_e32 v74, v5
	v_mov_b32_e32 v73, v5
	v_mov_b32_e32 v72, v5
	v_mov_b32_e32 v71, v5
	v_mov_b32_e32 v70, v5
	v_mov_b32_e32 v69, v5
	v_mov_b32_e32 v68, v5
	v_mov_b32_e32 v67, v5
	v_mov_b32_e32 v66, v5
	s_barrier
	s_cbranch_scc1 .LBB0_262
	v_lshlrev_b32_e32 v2, 6, v130
	s_add_i32 s59, s33, -2
	v_add3_u32 v2, v131, s60, v2
	s_cmp_eq_u32 s97, 1
	v_mad_i64_i32 v[2:3], s[46:47], v2, s62, 0
	s_cselect_b64 s[30:31], -1, 0
	v_lshrrev_b32_e32 v5, 1, v204
	s_lshl_b64 s[46:47], s[94:95], 1
	v_and_b32_e32 v4, 0xc0, v204
	v_and_b32_e32 v5, 24, v5
	s_add_u32 s46, s15, s46
	v_or3_b32 v2, v2, v4, v5
	s_addc_u32 s47, s16, s47
	v_mov_b32_e32 v66, 0
	v_lshl_add_u64 v[130:131], s[46:47], 0, v[2:3]
	s_mov_b32 s2, 0
	s_movk_i32 s70, 0x100
	v_mov_b32_e32 v67, v66
	v_mov_b32_e32 v68, v66
	v_mov_b32_e32 v69, v66
	v_mov_b32_e32 v70, v66
	v_mov_b32_e32 v71, v66
	v_mov_b32_e32 v72, v66
	v_mov_b32_e32 v73, v66
	v_mov_b32_e32 v74, v66
	v_mov_b32_e32 v75, v66
	v_mov_b32_e32 v76, v66
	v_mov_b32_e32 v77, v66
	v_mov_b32_e32 v78, v66
	v_mov_b32_e32 v79, v66
	v_mov_b32_e32 v80, v66
	v_mov_b32_e32 v81, v66
	v_mov_b32_e32 v82, v66
	v_mov_b32_e32 v83, v66
	v_mov_b32_e32 v84, v66
	v_mov_b32_e32 v85, v66
	v_mov_b32_e32 v86, v66
	v_mov_b32_e32 v87, v66
	v_mov_b32_e32 v88, v66
	v_mov_b32_e32 v89, v66
	v_mov_b32_e32 v90, v66
	v_mov_b32_e32 v91, v66
	v_mov_b32_e32 v92, v66
	v_mov_b32_e32 v93, v66
	v_mov_b32_e32 v94, v66
	v_mov_b32_e32 v95, v66
	v_mov_b32_e32 v96, v66
	v_mov_b32_e32 v97, v66
	v_mov_b32_e32 v98, v66
	v_mov_b32_e32 v99, v66
	v_mov_b32_e32 v100, v66
	v_mov_b32_e32 v101, v66
	v_mov_b32_e32 v102, v66
	v_mov_b32_e32 v103, v66
	v_mov_b32_e32 v104, v66
	v_mov_b32_e32 v105, v66
	v_mov_b32_e32 v106, v66
	v_mov_b32_e32 v107, v66
	v_mov_b32_e32 v108, v66
	v_mov_b32_e32 v109, v66
	v_mov_b32_e32 v110, v66
	v_mov_b32_e32 v111, v66
	v_mov_b32_e32 v112, v66
	v_mov_b32_e32 v113, v66
	v_mov_b32_e32 v114, v66
	v_mov_b32_e32 v115, v66
	v_mov_b32_e32 v116, v66
	v_mov_b32_e32 v117, v66
	v_mov_b32_e32 v118, v66
	v_mov_b32_e32 v119, v66
	v_mov_b32_e32 v120, v66
	v_mov_b32_e32 v121, v66
	v_mov_b32_e32 v122, v66
	v_mov_b32_e32 v123, v66
	v_mov_b32_e32 v124, v66
	v_mov_b32_e32 v125, v66
	v_mov_b32_e32 v126, v66
	v_mov_b32_e32 v127, v66
	v_mov_b32_e32 v128, v66
	v_mov_b32_e32 v129, v66
	v_mov_b32_e32 v62, v66
	v_mov_b32_e32 v63, v66
	v_mov_b32_e32 v64, v66
	v_mov_b32_e32 v65, v66
	v_mov_b32_e32 v58, v66
	v_mov_b32_e32 v59, v66
	v_mov_b32_e32 v60, v66
	v_mov_b32_e32 v61, v66
	v_mov_b32_e32 v54, v66
	v_mov_b32_e32 v55, v66
	v_mov_b32_e32 v56, v66
	v_mov_b32_e32 v57, v66
	v_mov_b32_e32 v50, v66
	v_mov_b32_e32 v51, v66
	v_mov_b32_e32 v52, v66
	v_mov_b32_e32 v53, v66
	v_mov_b32_e32 v46, v66
	v_mov_b32_e32 v47, v66
	v_mov_b32_e32 v48, v66
	v_mov_b32_e32 v49, v66
	v_mov_b32_e32 v42, v66
	v_mov_b32_e32 v43, v66
	v_mov_b32_e32 v44, v66
	v_mov_b32_e32 v45, v66
	v_mov_b32_e32 v38, v66
	v_mov_b32_e32 v39, v66
	v_mov_b32_e32 v40, v66
	v_mov_b32_e32 v41, v66
	v_mov_b32_e32 v34, v66
	v_mov_b32_e32 v35, v66
	v_mov_b32_e32 v36, v66
	v_mov_b32_e32 v37, v66
	v_mov_b32_e32 v30, v66
	v_mov_b32_e32 v31, v66
	v_mov_b32_e32 v32, v66
	v_mov_b32_e32 v33, v66
	v_mov_b32_e32 v26, v66
	v_mov_b32_e32 v27, v66
	v_mov_b32_e32 v28, v66
	v_mov_b32_e32 v29, v66
	v_mov_b32_e32 v22, v66
	v_mov_b32_e32 v23, v66
	v_mov_b32_e32 v24, v66
	v_mov_b32_e32 v25, v66
	v_mov_b32_e32 v18, v66
	v_mov_b32_e32 v19, v66
	v_mov_b32_e32 v20, v66
	v_mov_b32_e32 v21, v66
	v_mov_b32_e32 v14, v66
	v_mov_b32_e32 v15, v66
	v_mov_b32_e32 v16, v66
	v_mov_b32_e32 v17, v66
	v_mov_b32_e32 v10, v66
	v_mov_b32_e32 v11, v66
	v_mov_b32_e32 v12, v66
	v_mov_b32_e32 v13, v66
	v_mov_b32_e32 v6, v66
	v_mov_b32_e32 v7, v66
	v_mov_b32_e32 v8, v66
	v_mov_b32_e32 v9, v66
	v_mov_b32_e32 v2, v66
	v_mov_b32_e32 v3, v66
	v_mov_b32_e32 v4, v66
	v_mov_b32_e32 v5, v66
	v_readfirstlane_b32 s46, v204
	s_nop 3
	s_lshr_b32 s46, s46, 8
	s_cmp_eq_u32 s46, 9
	s_cbranch_scc0 .Lgprio_done
	s_setprio 1
